# hyena: padded LDS layout for parked conv results (32-way bank conflict removed)
# speedup vs baseline: 1.0403x; 1.0074x over previous
.LBB0_532:
	v_mfma_f32_32x32x16_bf16 v[18:33], v[44:47], v[48:51], v[18:33]
	v_mfma_f32_32x32x16_bf16 v[2:17], v[44:47], v[92:95], v[2:17]
	v_mfma_f32_32x32x16_bf16 v[18:33], v[88:91], v[96:99], v[18:33]
	v_mfma_f32_32x32x16_bf16 v[2:17], v[88:91], v[100:103], v[2:17]
	s_add_i32 s7, s7, -1
	v_add_u32_e32 v52, v40, v39
	ds_read_u16 v104, v52
	ds_read_u16 v105, v52 offset:2
	ds_read_u16 v106, v52 offset:4
	ds_read_u16 v107, v52 offset:6
	ds_read_u16 v108, v52 offset:8
	ds_read_u16 v109, v52 offset:10
	ds_read_u16 v110, v52 offset:12
	ds_read_u16 v111, v52 offset:14
	v_cmp_lt_i32_e32 vcc, -1, v43
	v_cmp_gt_i32_e64 s[40:41], s6, v43
	v_add_u32_e32 v53, v42, v39
	v_add_u32_e32 v55, v41, v39
	s_and_b64 vcc, vcc, s[40:41]
	v_add_u32_e32 v120, 0xffc0, v53
	v_add_u32_e32 v121, 0xffc0, v55
	v_add_u32_e32 v122, 0xffe0, v53
	v_add_u32_e32 v123, 0xffe0, v55
	v_cndmask_b32_e32 v120, v54, v120, vcc
	v_cndmask_b32_e32 v121, v54, v121, vcc
	v_cndmask_b32_e32 v122, v54, v122, vcc
	v_cndmask_b32_e32 v123, v54, v123, vcc
	ds_read_b128 v[48:51], v120
	ds_read_b128 v[92:95], v121
	ds_read_b128 v[96:99], v122
	ds_read_b128 v[100:103], v123
	s_waitcnt lgkmcnt(7)
	ds_read_u16 v112, v52 offset:32
	ds_read_u16 v113, v52 offset:34
	ds_read_u16 v114, v52 offset:36
	ds_read_u16 v115, v52 offset:38
	ds_read_u16 v116, v52 offset:40
	ds_read_u16 v117, v52 offset:42
	ds_read_u16 v118, v52 offset:44
	ds_read_u16 v119, v52 offset:46
	v_subrev_u32_e32 v40, 64, v40
	v_subrev_u32_e32 v41, 64, v41
	v_subrev_u32_e32 v42, 64, v42
	v_add_u32_e32 v43, -1, v43
	s_waitcnt lgkmcnt(0)
	v_perm_b32 v44, v105, v104, s86
	v_perm_b32 v45, v107, v106, s86
	v_perm_b32 v46, v109, v108, s86
	v_perm_b32 v47, v111, v110, s86
	v_perm_b32 v88, v113, v112, s86
	v_perm_b32 v89, v115, v114, s86
	v_perm_b32 v90, v117, v116, s86
	v_perm_b32 v91, v119, v118, s86
	s_cmp_lg_u32 s7, 0
	s_cbranch_scc1 .LBB0_532
	s_barrier
	v_lshlrev_b32_e32 v37, 5, v37
	v_lshlrev_b32_e32 v36, 2, v36
	v_add_u32_e32 v38, v38, v37
	v_lshl_add_u32 v35, v35, 1, 0
	v_or_b32_e32 v38, v38, v36
	v_bfe_u32 v39, v18, 16, 1
	v_add3_u32 v18, v18, v39, s27
	v_lshrrev_b32_e32 v56, 5, v38
	v_lshl_add_u32 v38, v38, 4, v35
	v_lshl_add_u32 v38, v56, 4, v38
	ds_write_b16_d16_hi v38, v18
	v_bfe_u32 v18, v19, 16, 1
	v_add3_u32 v18, v19, v18, s27
	ds_write_b16_d16_hi v38, v18 offset:16
	v_bfe_u32 v18, v20, 16, 1
	v_add3_u32 v18, v20, v18, s27
	ds_write_b16_d16_hi v38, v18 offset:32
	v_bfe_u32 v18, v21, 16, 1
	v_add3_u32 v18, v21, v18, s27
	ds_write_b16_d16_hi v38, v18 offset:48
	v_bfe_u32 v18, v22, 16, 1
	v_add3_u32 v18, v22, v18, s27
	ds_write_b16_d16_hi v38, v18 offset:128
	v_bfe_u32 v18, v23, 16, 1
	v_add3_u32 v18, v23, v18, s27
	ds_write_b16_d16_hi v38, v18 offset:144
	v_bfe_u32 v18, v24, 16, 1
	v_add3_u32 v18, v24, v18, s27
	ds_write_b16_d16_hi v38, v18 offset:160
	v_bfe_u32 v18, v25, 16, 1
	v_add3_u32 v18, v25, v18, s27
	ds_write_b16_d16_hi v38, v18 offset:176
	v_bfe_u32 v18, v26, 16, 1
	v_add3_u32 v18, v26, v18, s27
	ds_write_b16_d16_hi v38, v18 offset:256
	v_bfe_u32 v18, v27, 16, 1
	v_add3_u32 v18, v27, v18, s27
	ds_write_b16_d16_hi v38, v18 offset:272
	v_bfe_u32 v18, v28, 16, 1
	v_add3_u32 v18, v28, v18, s27
	ds_write_b16_d16_hi v38, v18 offset:288
	v_bfe_u32 v18, v29, 16, 1
	v_add3_u32 v18, v29, v18, s27
	ds_write_b16_d16_hi v38, v18 offset:304
	v_bfe_u32 v18, v30, 16, 1
	v_add3_u32 v18, v30, v18, s27
	ds_write_b16_d16_hi v38, v18 offset:384
	v_bfe_u32 v18, v31, 16, 1
	v_add3_u32 v18, v31, v18, s27
	ds_write_b16_d16_hi v38, v18 offset:400
	v_bfe_u32 v18, v32, 16, 1
	v_add3_u32 v18, v32, v18, s27
	ds_write_b16_d16_hi v38, v18 offset:416
	v_bfe_u32 v18, v33, 16, 1
	v_add3_u32 v18, v33, v18, s27
	v_add_u32_e32 v0, v0, v37
	ds_write_b16_d16_hi v38, v18 offset:432
	v_or_b32_e32 v0, v0, v36
	v_bfe_u32 v18, v2, 16, 1
	v_add3_u32 v2, v2, v18, s27
	v_lshrrev_b32_e32 v57, 5, v0
	v_lshl_add_u32 v0, v0, 4, v35
	v_lshl_add_u32 v0, v57, 4, v0
	ds_write_b16_d16_hi v0, v2
	v_bfe_u32 v2, v3, 16, 1
	v_add3_u32 v2, v3, v2, s27
	ds_write_b16_d16_hi v0, v2 offset:16
	v_bfe_u32 v2, v4, 16, 1
	v_add3_u32 v2, v4, v2, s27
	ds_write_b16_d16_hi v0, v2 offset:32
	v_bfe_u32 v2, v5, 16, 1
	v_add3_u32 v2, v5, v2, s27
	ds_write_b16_d16_hi v0, v2 offset:48
	v_bfe_u32 v2, v6, 16, 1
	v_add3_u32 v2, v6, v2, s27
	ds_write_b16_d16_hi v0, v2 offset:128
	v_bfe_u32 v2, v7, 16, 1
	v_add3_u32 v2, v7, v2, s27
	ds_write_b16_d16_hi v0, v2 offset:144
	v_bfe_u32 v2, v8, 16, 1
	v_add3_u32 v2, v8, v2, s27
	ds_write_b16_d16_hi v0, v2 offset:160
	v_bfe_u32 v2, v9, 16, 1
	v_add3_u32 v2, v9, v2, s27
	ds_write_b16_d16_hi v0, v2 offset:176
	v_bfe_u32 v2, v10, 16, 1
	v_add3_u32 v2, v10, v2, s27
	ds_write_b16_d16_hi v0, v2 offset:256
	v_bfe_u32 v2, v11, 16, 1
	v_add3_u32 v2, v11, v2, s27
	ds_write_b16_d16_hi v0, v2 offset:272
	v_bfe_u32 v2, v12, 16, 1
	v_add3_u32 v2, v12, v2, s27
	ds_write_b16_d16_hi v0, v2 offset:288
	v_bfe_u32 v2, v13, 16, 1
	v_add3_u32 v2, v13, v2, s27
	ds_write_b16_d16_hi v0, v2 offset:304
	v_bfe_u32 v2, v14, 16, 1
	v_add3_u32 v2, v14, v2, s27
	ds_write_b16_d16_hi v0, v2 offset:384
	v_bfe_u32 v2, v15, 16, 1
	v_add3_u32 v2, v15, v2, s27
	ds_write_b16_d16_hi v0, v2 offset:400
	v_bfe_u32 v2, v16, 16, 1
	v_add3_u32 v2, v16, v2, s27
	ds_write_b16_d16_hi v0, v2 offset:416
	v_bfe_u32 v2, v17, 16, 1
	s_movk_i32 s4, 0x800
	v_add3_u32 v2, v17, v2, s27
	v_cmp_gt_i32_e32 vcc, s4, v34
	ds_write_b16_d16_hi v0, v2 offset:432
	s_waitcnt lgkmcnt(0)
	s_barrier
	s_and_saveexec_b64 s[40:41], vcc
	s_mov_b64 s[10:11], 0x100000
	s_cbranch_execz .LBB0_497
	s_add_i32 s4, s38, s3
	s_ashr_i32 s5, s4, 31
	s_lshl_b64 s[4:5], s[4:5], 2
	s_add_u32 s4, s42, s4
	s_addc_u32 s5, s43, s5
	global_load_dwordx4 v[2:5], v1, s[4:5] offset:16
	global_load_dwordx4 v[6:9], v1, s[4:5]
	s_ashr_i32 s39, s38, 31
	v_add_u32_e32 v12, s44, v34
	s_lshl_b64 s[4:5], s[38:39], 1
	v_readlane_b32 s6, v253, 50
	v_ashrrev_i32_e32 v13, 31, v12
	v_readlane_b32 s7, v253, 51
	s_add_u32 s6, s6, s4
	v_lshlrev_b64 v[10:11], 11, v[12:13]
	s_addc_u32 s7, s7, s5
	v_lshl_add_u64 v[10:11], s[6:7], 0, v[10:11]
	v_readlane_b32 s6, v254, 49
	v_readlane_b32 s7, v254, 50
	s_add_u32 s4, s6, s4
	v_lshlrev_b64 v[12:13], 10, v[12:13]
	s_addc_u32 s5, s7, s5
	v_add_u32_e32 v0, 0xfffffe00, v34
	v_lshl_add_u32 v14, v34, 4, 0
	v_lshrrev_b32_e32 v15, 5, v34
	v_lshl_add_u32 v14, v15, 4, v14
	v_lshl_add_u64 v[12:13], s[4:5], 0, v[12:13]
	s_mov_b64 s[38:39], 0
	s_mov_b64 s[4:5], 0x80000
	global_load_dwordx4 v[56:59], v[12:13], off
	v_add_co_u32_e32 v24, vcc, 0x600000, v12
	s_nop 1
	v_addc_co_u32_e32 v25, vcc, 0, v13, vcc
	global_load_dwordx4 v[72:75], v[24:25], off
	ds_read_b128 v[88:91], v14
	v_lshl_add_u64 v[12:13], v[12:13], 0, s[4:5]
	global_load_dwordx4 v[60:63], v[12:13], off
	v_add_co_u32_e32 v24, vcc, 0x600000, v12
	s_nop 1
	v_addc_co_u32_e32 v25, vcc, 0, v13, vcc
	global_load_dwordx4 v[76:79], v[24:25], off
	ds_read_b128 v[92:95], v14 offset:8448
	v_lshl_add_u64 v[12:13], v[12:13], 0, s[4:5]
	global_load_dwordx4 v[64:67], v[12:13], off
	v_add_co_u32_e32 v24, vcc, 0x600000, v12
	s_nop 1
	v_addc_co_u32_e32 v25, vcc, 0, v13, vcc
	global_load_dwordx4 v[80:83], v[24:25], off
	ds_read_b128 v[96:99], v14 offset:16896
	v_lshl_add_u64 v[12:13], v[12:13], 0, s[4:5]
	global_load_dwordx4 v[68:71], v[12:13], off
	v_add_co_u32_e32 v24, vcc, 0x600000, v12
	s_nop 1
	v_addc_co_u32_e32 v25, vcc, 0, v13, vcc
	global_load_dwordx4 v[84:87], v[24:25], off
	ds_read_b128 v[100:103], v14 offset:25344
	v_lshl_add_u64 v[12:13], v[12:13], 0, s[4:5]
	s_waitcnt vmcnt(6) lgkmcnt(3)
	v_mov_b32_e32 v16, v88
	v_mov_b32_e32 v17, v89
	v_mov_b32_e32 v18, v90
	v_mov_b32_e32 v19, v91
	v_mov_b32_e32 v20, v56
	v_mov_b32_e32 v21, v57
	v_mov_b32_e32 v22, v58
	v_mov_b32_e32 v23, v59
	v_mov_b32_e32 v24, v72
	v_mov_b32_e32 v25, v73
	v_mov_b32_e32 v26, v74
	v_mov_b32_e32 v27, v75
	v_and_b32_e32 v31, 0xffff0000, v16
	v_lshlrev_b32_e32 v30, 16, v16
	v_and_b32_e32 v29, 0xffff0000, v20
	v_lshlrev_b32_e32 v28, 16, v20
	v_lshlrev_b32_e32 v20, 16, v17
	v_and_b32_e32 v33, 0xffff0000, v24
	v_lshlrev_b32_e32 v32, 16, v24
	v_pk_fma_f32 v[30:31], v[6:7], v[32:33], v[30:31]
	v_lshlrev_b32_e32 v16, 16, v25
	v_pk_mul_f32 v[28:29], v[30:31], v[28:29]
	v_and_b32_e32 v31, 0xffff0000, v21
	v_lshlrev_b32_e32 v30, 16, v21
	v_and_b32_e32 v21, 0xffff0000, v17
	v_and_b32_e32 v17, 0xffff0000, v25
	v_pk_fma_f32 v[16:17], v[8:9], v[16:17], v[20:21]
	v_and_b32_e32 v25, 0xffff0000, v18
	v_pk_mul_f32 v[20:21], v[16:17], v[30:31]
	v_lshlrev_b32_e32 v24, 16, v18
	v_and_b32_e32 v31, 0xffff0000, v26
	v_lshlrev_b32_e32 v30, 16, v26
	v_and_b32_e32 v17, 0xffff0000, v22
	v_lshlrev_b32_e32 v16, 16, v22
	v_pk_fma_f32 v[24:25], v[2:3], v[30:31], v[24:25]
	v_lshlrev_b32_e32 v22, 16, v19
	v_pk_mul_f32 v[24:25], v[24:25], v[16:17]
	v_and_b32_e32 v17, 0xffff0000, v23
	v_lshlrev_b32_e32 v16, 16, v23
	v_and_b32_e32 v23, 0xffff0000, v19
	v_and_b32_e32 v19, 0xffff0000, v27
	v_lshlrev_b32_e32 v18, 16, v27
	v_pk_fma_f32 v[18:19], v[4:5], v[18:19], v[22:23]
	s_nop 0
	v_pk_mul_f32 v[22:23], v[18:19], v[16:17]
	v_cvt_pk_bf16_f32 v16, v28, v29
	v_cvt_pk_bf16_f32 v17, v20, v21
	v_cvt_pk_bf16_f32 v18, v24, v25
	v_cvt_pk_bf16_f32 v19, v22, v23
	global_store_dwordx4 v[10:11], v[16:19], off
	v_lshl_add_u64 v[10:11], v[10:11], 0, s[10:11]
	s_nop 1
	s_waitcnt vmcnt(5) lgkmcnt(2)
	v_mov_b32_e32 v16, v92
	v_mov_b32_e32 v17, v93
	v_mov_b32_e32 v18, v94
	v_mov_b32_e32 v19, v95
	v_mov_b32_e32 v20, v60
	v_mov_b32_e32 v21, v61
	v_mov_b32_e32 v22, v62
	v_mov_b32_e32 v23, v63
	v_mov_b32_e32 v24, v76
	v_mov_b32_e32 v25, v77
	v_mov_b32_e32 v26, v78
	v_mov_b32_e32 v27, v79
	v_and_b32_e32 v31, 0xffff0000, v16
	v_lshlrev_b32_e32 v30, 16, v16
	v_and_b32_e32 v29, 0xffff0000, v20
	v_lshlrev_b32_e32 v28, 16, v20
	v_lshlrev_b32_e32 v20, 16, v17
	v_and_b32_e32 v33, 0xffff0000, v24
	v_lshlrev_b32_e32 v32, 16, v24
	v_pk_fma_f32 v[30:31], v[6:7], v[32:33], v[30:31]
	v_lshlrev_b32_e32 v16, 16, v25
	v_pk_mul_f32 v[28:29], v[30:31], v[28:29]
	v_and_b32_e32 v31, 0xffff0000, v21
	v_lshlrev_b32_e32 v30, 16, v21
	v_and_b32_e32 v21, 0xffff0000, v17
	v_and_b32_e32 v17, 0xffff0000, v25
	v_pk_fma_f32 v[16:17], v[8:9], v[16:17], v[20:21]
	v_and_b32_e32 v25, 0xffff0000, v18
	v_pk_mul_f32 v[20:21], v[16:17], v[30:31]
	v_lshlrev_b32_e32 v24, 16, v18
	v_and_b32_e32 v31, 0xffff0000, v26
	v_lshlrev_b32_e32 v30, 16, v26
	v_and_b32_e32 v17, 0xffff0000, v22
	v_lshlrev_b32_e32 v16, 16, v22
	v_pk_fma_f32 v[24:25], v[2:3], v[30:31], v[24:25]
	v_lshlrev_b32_e32 v22, 16, v19
	v_pk_mul_f32 v[24:25], v[24:25], v[16:17]
	v_and_b32_e32 v17, 0xffff0000, v23
	v_lshlrev_b32_e32 v16, 16, v23
	v_and_b32_e32 v23, 0xffff0000, v19
	v_and_b32_e32 v19, 0xffff0000, v27
	v_lshlrev_b32_e32 v18, 16, v27
	v_pk_fma_f32 v[18:19], v[4:5], v[18:19], v[22:23]
	s_nop 0
	v_pk_mul_f32 v[22:23], v[18:19], v[16:17]
	v_cvt_pk_bf16_f32 v16, v28, v29
	v_cvt_pk_bf16_f32 v17, v20, v21
	v_cvt_pk_bf16_f32 v18, v24, v25
	v_cvt_pk_bf16_f32 v19, v22, v23
	global_store_dwordx4 v[10:11], v[16:19], off
	v_lshl_add_u64 v[10:11], v[10:11], 0, s[10:11]
	s_nop 1
	s_waitcnt vmcnt(4) lgkmcnt(1)
	v_mov_b32_e32 v16, v96
	v_mov_b32_e32 v17, v97
	v_mov_b32_e32 v18, v98
	v_mov_b32_e32 v19, v99
	v_mov_b32_e32 v20, v64
	v_mov_b32_e32 v21, v65
	v_mov_b32_e32 v22, v66
	v_mov_b32_e32 v23, v67
	v_mov_b32_e32 v24, v80
	v_mov_b32_e32 v25, v81
	v_mov_b32_e32 v26, v82
	v_mov_b32_e32 v27, v83
	v_and_b32_e32 v31, 0xffff0000, v16
	v_lshlrev_b32_e32 v30, 16, v16
	v_and_b32_e32 v29, 0xffff0000, v20
	v_lshlrev_b32_e32 v28, 16, v20
	v_lshlrev_b32_e32 v20, 16, v17
	v_and_b32_e32 v33, 0xffff0000, v24
	v_lshlrev_b32_e32 v32, 16, v24
	v_pk_fma_f32 v[30:31], v[6:7], v[32:33], v[30:31]
	v_lshlrev_b32_e32 v16, 16, v25
	v_pk_mul_f32 v[28:29], v[30:31], v[28:29]
	v_and_b32_e32 v31, 0xffff0000, v21
	v_lshlrev_b32_e32 v30, 16, v21
	v_and_b32_e32 v21, 0xffff0000, v17
	v_and_b32_e32 v17, 0xffff0000, v25
	v_pk_fma_f32 v[16:17], v[8:9], v[16:17], v[20:21]
	v_and_b32_e32 v25, 0xffff0000, v18
	v_pk_mul_f32 v[20:21], v[16:17], v[30:31]
	v_lshlrev_b32_e32 v24, 16, v18
	v_and_b32_e32 v31, 0xffff0000, v26
	v_lshlrev_b32_e32 v30, 16, v26
	v_and_b32_e32 v17, 0xffff0000, v22
	v_lshlrev_b32_e32 v16, 16, v22
	v_pk_fma_f32 v[24:25], v[2:3], v[30:31], v[24:25]
	v_lshlrev_b32_e32 v22, 16, v19
	v_pk_mul_f32 v[24:25], v[24:25], v[16:17]
	v_and_b32_e32 v17, 0xffff0000, v23
	v_lshlrev_b32_e32 v16, 16, v23
	v_and_b32_e32 v23, 0xffff0000, v19
	v_and_b32_e32 v19, 0xffff0000, v27
	v_lshlrev_b32_e32 v18, 16, v27
	v_pk_fma_f32 v[18:19], v[4:5], v[18:19], v[22:23]
	s_nop 0
	v_pk_mul_f32 v[22:23], v[18:19], v[16:17]
	v_cvt_pk_bf16_f32 v16, v28, v29
	v_cvt_pk_bf16_f32 v17, v20, v21
	v_cvt_pk_bf16_f32 v18, v24, v25
	v_cvt_pk_bf16_f32 v19, v22, v23
	global_store_dwordx4 v[10:11], v[16:19], off
	v_lshl_add_u64 v[10:11], v[10:11], 0, s[10:11]
	s_nop 1
	s_waitcnt vmcnt(3) lgkmcnt(0)
	v_mov_b32_e32 v16, v100
	v_mov_b32_e32 v17, v101
	v_mov_b32_e32 v18, v102
	v_mov_b32_e32 v19, v103
	v_mov_b32_e32 v20, v68
	v_mov_b32_e32 v21, v69
	v_mov_b32_e32 v22, v70
	v_mov_b32_e32 v23, v71
	v_mov_b32_e32 v24, v84
	v_mov_b32_e32 v25, v85
	v_mov_b32_e32 v26, v86
	v_mov_b32_e32 v27, v87
	v_and_b32_e32 v31, 0xffff0000, v16
	v_lshlrev_b32_e32 v30, 16, v16
	v_and_b32_e32 v29, 0xffff0000, v20
	v_lshlrev_b32_e32 v28, 16, v20
	v_lshlrev_b32_e32 v20, 16, v17
	v_and_b32_e32 v33, 0xffff0000, v24
	v_lshlrev_b32_e32 v32, 16, v24
	v_pk_fma_f32 v[30:31], v[6:7], v[32:33], v[30:31]
	v_lshlrev_b32_e32 v16, 16, v25
	v_pk_mul_f32 v[28:29], v[30:31], v[28:29]
	v_and_b32_e32 v31, 0xffff0000, v21
	v_lshlrev_b32_e32 v30, 16, v21
	v_and_b32_e32 v21, 0xffff0000, v17
	v_and_b32_e32 v17, 0xffff0000, v25
	v_pk_fma_f32 v[16:17], v[8:9], v[16:17], v[20:21]
	v_and_b32_e32 v25, 0xffff0000, v18
	v_pk_mul_f32 v[20:21], v[16:17], v[30:31]
	v_lshlrev_b32_e32 v24, 16, v18
	v_and_b32_e32 v31, 0xffff0000, v26
	v_lshlrev_b32_e32 v30, 16, v26
	v_and_b32_e32 v17, 0xffff0000, v22
	v_lshlrev_b32_e32 v16, 16, v22
	v_pk_fma_f32 v[24:25], v[2:3], v[30:31], v[24:25]
	v_lshlrev_b32_e32 v22, 16, v19
	v_pk_mul_f32 v[24:25], v[24:25], v[16:17]
	v_and_b32_e32 v17, 0xffff0000, v23
	v_lshlrev_b32_e32 v16, 16, v23
	v_and_b32_e32 v23, 0xffff0000, v19
	v_and_b32_e32 v19, 0xffff0000, v27
	v_lshlrev_b32_e32 v18, 16, v27
	v_pk_fma_f32 v[18:19], v[4:5], v[18:19], v[22:23]
	s_nop 0
	v_pk_mul_f32 v[22:23], v[18:19], v[16:17]
	v_cvt_pk_bf16_f32 v16, v28, v29
	v_cvt_pk_bf16_f32 v17, v20, v21
	v_cvt_pk_bf16_f32 v18, v24, v25
	v_cvt_pk_bf16_f32 v19, v22, v23
	global_store_dwordx4 v[10:11], v[16:19], off
	v_lshl_add_u64 v[10:11], v[10:11], 0, s[10:11]
	s_nop 1
	s_branch .LBB0_497
